# RG-LRU pass 1 (a, bx, chunk carries): counted vmcnt waits in front of the first use of each of the 48 loads of a 16-token block instead of one vmcnt(0)
# baseline (speedup 1.0000x reference)
; __device__ __forceinline__ float bf2f(bf16 b) { return __uint_as_float(((unsigned)b) << 16); }
; __device__ __forceinline__ void stage_lruA(const Params& P) {
;     ...
;         for (int tb = c * LCH; tb < (c + 1) * LCH; tb += 16) {
;             float la[16], ig[16], uc[16];
; #pragma unroll
;             for (int i = 0; i < 16; ++i) { la[i] = LA[(size_t)(tb + i) * 512 + ch]; ig[i] = LBX[(size_t)(tb + i) * 512 + ch]; uc[i] = bf2f(UC[(size_t)(tb + i) * 512 + ch]); }
; #pragma unroll
;             for (int i = 0; i < 16; ++i) {
;                 const float a = __expf(la[i]), x2 = 2.f * la[i];
;                 const float em = x2 > -0.1f ? -x2 * (1.f + x2 * (0.5f + x2 * (0.16666667f + x2 * 0.041666668f))) : 1.f - __expf(x2);
;                 const float mult = (tb + i) == 0 ? 1.f : __builtin_amdgcn_sqrtf(em);
;                 const float bxv = mult * ig[i] * uc[i];
;                 hh = a * hh + bxv; ap *= a;
;                 LA[(size_t)(tb + i) * 512 + ch] = a; LBX[(size_t)(tb + i) * 512 + ch] = bxv;
.LBB0_279:
	v_lshl_add_u64 v[4:5], s[72:73], 0, v[0:1]
	v_add_co_u32_e32 v12, vcc, 0xb080000, v4
	v_lshl_add_u64 v[6:7], s[72:73], 0, v[2:3]
	s_nop 0
	v_addc_co_u32_e32 v13, vcc, 0, v5, vcc
	v_add_co_u32_e32 v14, vcc, 0xd080000, v4
	global_load_dword v19, v[12:13], off
	s_nop 0
	v_addc_co_u32_e32 v15, vcc, 0, v5, vcc
	v_add_co_u32_e32 v16, vcc, 0x11200000, v6
	global_load_dword v20, v[14:15], off
	s_nop 0
	v_addc_co_u32_e32 v17, vcc, 0, v7, vcc
	global_load_ushort v56, v[16:17], off
	global_load_dword v28, v[12:13], off offset:2048
	global_load_dword v29, v[14:15], off offset:2048
	global_load_ushort v55, v[16:17], off offset:1024
	v_add_co_u32_e32 v12, vcc, 0xb081000, v4
	s_nop 1
	v_addc_co_u32_e32 v13, vcc, 0, v5, vcc
	v_add_co_u32_e32 v14, vcc, 0xd081000, v4
	global_load_dword v36, v[12:13], off
	s_nop 0
	v_addc_co_u32_e32 v15, vcc, 0, v5, vcc
	global_load_dword v37, v[14:15], off
	global_load_ushort v54, v[16:17], off offset:2048
	global_load_dword v42, v[12:13], off offset:2048
	global_load_dword v44, v[14:15], off offset:2048
	global_load_ushort v51, v[16:17], off offset:3072
	v_add_co_u32_e32 v12, vcc, 0xb082000, v4
	s_nop 1
	v_addc_co_u32_e32 v13, vcc, 0, v5, vcc
	v_add_co_u32_e32 v14, vcc, 0xd082000, v4
	global_load_dword v50, v[12:13], off
	s_nop 0
	v_addc_co_u32_e32 v15, vcc, 0, v5, vcc
	v_add_co_u32_e32 v16, vcc, 0x11201000, v6
	global_load_dword v52, v[14:15], off
	s_nop 0
	v_addc_co_u32_e32 v17, vcc, 0, v7, vcc
	global_load_ushort v53, v[16:17], off
	global_load_dword v45, v[12:13], off offset:2048
	global_load_dword v48, v[14:15], off offset:2048
	global_load_ushort v49, v[16:17], off offset:1024
	v_add_co_u32_e32 v12, vcc, 0xb083000, v4
	s_nop 1
	v_addc_co_u32_e32 v13, vcc, 0, v5, vcc
	v_add_co_u32_e32 v14, vcc, 0xd083000, v4
	global_load_dword v43, v[12:13], off
	s_nop 0
	v_addc_co_u32_e32 v15, vcc, 0, v5, vcc
	global_load_dword v46, v[14:15], off
	global_load_ushort v47, v[16:17], off offset:2048
	global_load_dword v39, v[12:13], off offset:2048
	global_load_dword v40, v[14:15], off offset:2048
	global_load_ushort v41, v[16:17], off offset:3072
	v_add_co_u32_e32 v12, vcc, 0xb084000, v4
	s_nop 1
	v_addc_co_u32_e32 v13, vcc, 0, v5, vcc
	v_add_co_u32_e32 v14, vcc, 0xd084000, v4
	global_load_dword v34, v[12:13], off
	s_nop 0
	v_addc_co_u32_e32 v15, vcc, 0, v5, vcc
	v_add_co_u32_e32 v16, vcc, 0x11202000, v6
	global_load_dword v35, v[14:15], off
	s_nop 0
	v_addc_co_u32_e32 v17, vcc, 0, v7, vcc
	global_load_ushort v38, v[16:17], off
	global_load_dword v32, v[12:13], off offset:2048
	global_load_dword v31, v[14:15], off offset:2048
	global_load_ushort v33, v[16:17], off offset:1024
	v_add_co_u32_e32 v12, vcc, 0xb085000, v4
	s_nop 1
	v_addc_co_u32_e32 v13, vcc, 0, v5, vcc
	v_add_co_u32_e32 v14, vcc, 0xd085000, v4
	global_load_dword v25, v[12:13], off
	s_nop 0
	v_addc_co_u32_e32 v15, vcc, 0, v5, vcc
	global_load_dword v26, v[14:15], off
	global_load_ushort v30, v[16:17], off offset:2048
	global_load_dword v22, v[12:13], off offset:2048
	global_load_dword v21, v[14:15], off offset:2048
	global_load_ushort v23, v[16:17], off offset:3072
	v_add_co_u32_e32 v12, vcc, 0xb086000, v4
	s_nop 1
	v_addc_co_u32_e32 v13, vcc, 0, v5, vcc
	v_add_co_u32_e32 v14, vcc, 0xd086000, v4
	global_load_dword v18, v[12:13], off
	s_nop 0
	v_addc_co_u32_e32 v15, vcc, 0, v5, vcc
	v_add_co_u32_e32 v58, vcc, 0x11203000, v6
	global_load_dword v24, v[14:15], off
	s_nop 0
	v_addc_co_u32_e32 v59, vcc, 0, v7, vcc
	v_add_co_u32_e32 v60, vcc, 0xb087000, v4
	global_load_ushort v27, v[58:59], off
	s_nop 0
	global_load_dword v13, v[12:13], off offset:2048
	s_nop 0
	global_load_dword v16, v[14:15], off offset:2048
	global_load_ushort v17, v[58:59], off offset:1024
	v_addc_co_u32_e32 v61, vcc, 0, v5, vcc
	v_add_co_u32_e32 v62, vcc, 0xd087000, v4
	global_load_dword v6, v[60:61], off
	s_nop 0
	v_addc_co_u32_e32 v63, vcc, 0, v5, vcc
	global_load_dword v14, v[62:63], off
	global_load_ushort v15, v[58:59], off offset:2048
	global_load_dword v7, v[60:61], off offset:2048
	global_load_dword v11, v[62:63], off offset:2048
	global_load_ushort v12, v[58:59], off offset:3072
	s_waitcnt vmcnt(47)
	v_add_f32_e32 v58, v19, v19
	v_cmp_nlt_f32_e32 vcc, s95, v58
	s_and_saveexec_b64 s[8:9], vcc
	s_xor_b64 s[8:9], exec, s[8:9]
	v_mul_f32_e32 v57, 0x3fb8aa3b, v58
	v_exp_f32_e32 v57, v57
	s_nop 0
	v_sub_f32_e32 v57, 1.0, v57
	s_andn2_saveexec_b64 s[8:9], s[8:9]
	v_fmamk_f32 v57, v58, 0x3d2aaaab, v222
	v_fma_f32 v57, v58, v57, 0.5
	v_fma_f32 v57, v58, v57, 1.0
	v_mul_f32_e64 v57, v57, -v58
	s_or_b64 exec, exec, s[8:9]
	v_sqrt_f32_e32 v57, v57
	v_mul_f32_e32 v19, 0x3fb8aa3b, v19
	s_cmp_lg_u32 s6, 0
	v_exp_f32_e32 v19, v19
	s_cselect_b64 vcc, -1, 0
	v_cndmask_b32_e32 v57, 1.0, v57, vcc
	s_mov_b64 s[8:9], 0xb080000
	s_waitcnt vmcnt(45)
	v_lshlrev_b32_e32 v56, 16, v56
	v_mul_f32_e32 v20, v20, v57
	s_waitcnt vmcnt(44)
	v_add_f32_e32 v57, v28, v28
	v_lshl_add_u64 v[58:59], v[4:5], 0, s[8:9]
	s_mov_b64 s[8:9], 0xd080000
	v_mul_f32_e32 v20, v20, v56
	v_cmp_nlt_f32_e32 vcc, s95, v57
	v_lshl_add_u64 v[60:61], v[4:5], 0, s[8:9]
	global_store_dword v[58:59], v19, off
	global_store_dword v[60:61], v20, off
	s_and_saveexec_b64 s[8:9], vcc
	s_xor_b64 s[8:9], exec, s[8:9]
	v_mul_f32_e32 v56, 0x3fb8aa3b, v57
	v_exp_f32_e32 v56, v56
	s_nop 0
	v_sub_f32_e32 v56, 1.0, v56
	s_andn2_saveexec_b64 s[8:9], s[8:9]
	v_fmamk_f32 v56, v57, 0x3d2aaaab, v222
	v_fma_f32 v56, v57, v56, 0.5
	v_fma_f32 v56, v57, v56, 1.0
	v_mul_f32_e64 v56, v56, -v57
	s_or_b64 exec, exec, s[8:9]
	v_sqrt_f32_e32 v56, v56
	v_mul_f32_e32 v28, 0x3fb8aa3b, v28
	v_exp_f32_e32 v28, v28
	s_mov_b64 s[8:9], 0xb080800
	s_waitcnt vmcnt(44)
; __device__ __forceinline__ float bf2f(bf16 b) { return __uint_as_float(((unsigned)b) << 16); }
; __device__ __forceinline__ void stage_lruA(const Params& P) {
;     ...
;             for (int i = 0; i < 16; ++i) { la[i] = LA[(size_t)(tb + i) * 512 + ch]; ig[i] = LBX[(size_t)(tb + i) * 512 + ch]; uc[i] = bf2f(UC[(size_t)(tb + i) * 512 + ch]); }
; #pragma unroll
;             for (int i = 0; i < 16; ++i) {
;                 const float a = __expf(la[i]), x2 = 2.f * la[i];
;                 const float em = x2 > -0.1f ? -x2 * (1.f + x2 * (0.5f + x2 * (0.16666667f + x2 * 0.041666668f))) : 1.f - __expf(x2);
;                 const float mult = (tb + i) == 0 ? 1.f : __builtin_amdgcn_sqrtf(em);
;                 const float bxv = mult * ig[i] * uc[i];
;                 hh = a * hh + bxv; ap *= a;
;                 LA[(size_t)(tb + i) * 512 + ch] = a; LBX[(size_t)(tb + i) * 512 + ch] = bxv;
	v_lshlrev_b32_e32 v55, 16, v55
	v_mul_f32_e32 v29, v29, v56
	s_waitcnt vmcnt(43)
	v_add_f32_e32 v56, v36, v36
	v_lshl_add_u64 v[58:59], v[4:5], 0, s[8:9]
	s_mov_b64 s[8:9], 0xd080800
	v_mul_f32_e32 v29, v29, v55
	v_cmp_nlt_f32_e32 vcc, s95, v56
	v_lshl_add_u64 v[60:61], v[4:5], 0, s[8:9]
	global_store_dword v[58:59], v28, off
	global_store_dword v[60:61], v29, off
	s_and_saveexec_b64 s[8:9], vcc
	s_xor_b64 s[8:9], exec, s[8:9]
	v_mul_f32_e32 v55, 0x3fb8aa3b, v56
	v_exp_f32_e32 v55, v55
	s_nop 0
	v_sub_f32_e32 v55, 1.0, v55
	s_andn2_saveexec_b64 s[8:9], s[8:9]
	v_fmamk_f32 v55, v56, 0x3d2aaaab, v222
	v_fma_f32 v55, v56, v55, 0.5
	v_fma_f32 v55, v56, v55, 1.0
	v_mul_f32_e64 v55, v55, -v56
	s_or_b64 exec, exec, s[8:9]
	v_sqrt_f32_e32 v55, v55
	v_mul_f32_e32 v36, 0x3fb8aa3b, v36
	v_exp_f32_e32 v36, v36
	s_mov_b64 s[8:9], 0xb081000
	s_waitcnt vmcnt(43)
	v_lshlrev_b32_e32 v54, 16, v54
	v_mul_f32_e32 v37, v37, v55
	s_waitcnt vmcnt(42)
	v_add_f32_e32 v55, v42, v42
	v_lshl_add_u64 v[56:57], v[4:5], 0, s[8:9]
	s_mov_b64 s[8:9], 0xd081000
	v_mul_f32_e32 v37, v37, v54
	v_cmp_nlt_f32_e32 vcc, s95, v55
	v_lshl_add_u64 v[58:59], v[4:5], 0, s[8:9]
	global_store_dword v[56:57], v36, off
	global_store_dword v[58:59], v37, off
	s_and_saveexec_b64 s[8:9], vcc
	s_xor_b64 s[8:9], exec, s[8:9]
	v_mul_f32_e32 v54, 0x3fb8aa3b, v55
	v_exp_f32_e32 v54, v54
	s_nop 0
	v_sub_f32_e32 v54, 1.0, v54
	s_andn2_saveexec_b64 s[8:9], s[8:9]
	v_fmamk_f32 v54, v55, 0x3d2aaaab, v222
	v_fma_f32 v54, v55, v54, 0.5
	v_fma_f32 v54, v55, v54, 1.0
	v_mul_f32_e64 v54, v54, -v55
	s_or_b64 exec, exec, s[8:9]
	v_sqrt_f32_e32 v54, v54
	v_mul_f32_e32 v42, 0x3fb8aa3b, v42
	v_exp_f32_e32 v42, v42
	s_mov_b64 s[8:9], 0xb081800
	s_waitcnt vmcnt(42)
	v_lshlrev_b32_e32 v51, 16, v51
	v_mul_f32_e32 v44, v44, v54
	s_waitcnt vmcnt(41)
	v_add_f32_e32 v54, v50, v50
	v_lshl_add_u64 v[56:57], v[4:5], 0, s[8:9]
	s_mov_b64 s[8:9], 0xd081800
	v_mul_f32_e32 v44, v44, v51
	v_cmp_nlt_f32_e32 vcc, s95, v54
	v_lshl_add_u64 v[58:59], v[4:5], 0, s[8:9]
	global_store_dword v[56:57], v42, off
	global_store_dword v[58:59], v44, off
	s_and_saveexec_b64 s[8:9], vcc
	s_xor_b64 s[8:9], exec, s[8:9]
	v_mul_f32_e32 v51, 0x3fb8aa3b, v54
	v_exp_f32_e32 v51, v51
	s_nop 0
	v_sub_f32_e32 v51, 1.0, v51
	s_andn2_saveexec_b64 s[8:9], s[8:9]
	v_fmamk_f32 v51, v54, 0x3d2aaaab, v222
	v_fma_f32 v51, v54, v51, 0.5
	v_fma_f32 v51, v54, v51, 1.0
	v_mul_f32_e64 v51, v51, -v54
	s_or_b64 exec, exec, s[8:9]
	v_sqrt_f32_e32 v51, v51
	v_mul_f32_e32 v50, 0x3fb8aa3b, v50
	v_exp_f32_e32 v50, v50
	s_waitcnt vmcnt(41)
	v_lshlrev_b32_e32 v53, 16, v53
	v_mul_f32_e32 v51, v52, v51
	s_mov_b64 s[8:9], 0xb082000
	v_mul_f32_e32 v51, v51, v53
	s_waitcnt vmcnt(40)
	v_add_f32_e32 v53, v45, v45
	v_lshl_add_u64 v[54:55], v[4:5], 0, s[8:9]
	s_mov_b64 s[8:9], 0xd082000
	v_cmp_nlt_f32_e32 vcc, s95, v53
	v_lshl_add_u64 v[56:57], v[4:5], 0, s[8:9]
	global_store_dword v[54:55], v50, off
	global_store_dword v[56:57], v51, off
	s_and_saveexec_b64 s[8:9], vcc
	s_xor_b64 s[8:9], exec, s[8:9]
	v_mul_f32_e32 v52, 0x3fb8aa3b, v53
	v_exp_f32_e32 v52, v52
	s_nop 0
	v_sub_f32_e32 v52, 1.0, v52
	s_andn2_saveexec_b64 s[8:9], s[8:9]
	v_fmamk_f32 v52, v53, 0x3d2aaaab, v222
	v_fma_f32 v52, v53, v52, 0.5
	v_fma_f32 v52, v53, v52, 1.0
	v_mul_f32_e64 v52, v52, -v53
	s_or_b64 exec, exec, s[8:9]
	v_sqrt_f32_e32 v52, v52
	v_mul_f32_e32 v45, 0x3fb8aa3b, v45
	v_exp_f32_e32 v45, v45
	s_mov_b64 s[8:9], 0xb082800
	s_waitcnt vmcnt(40)
	v_lshlrev_b32_e32 v49, 16, v49
	v_mul_f32_e32 v48, v48, v52
	s_waitcnt vmcnt(39)
	v_add_f32_e32 v52, v43, v43
	v_lshl_add_u64 v[54:55], v[4:5], 0, s[8:9]
	s_mov_b64 s[8:9], 0xd082800
	v_mul_f32_e32 v48, v48, v49
	v_cmp_nlt_f32_e32 vcc, s95, v52
	v_lshl_add_u64 v[56:57], v[4:5], 0, s[8:9]
	global_store_dword v[54:55], v45, off
	global_store_dword v[56:57], v48, off
	s_and_saveexec_b64 s[8:9], vcc
	s_xor_b64 s[8:9], exec, s[8:9]
	v_mul_f32_e32 v49, 0x3fb8aa3b, v52
	v_exp_f32_e32 v49, v49
	s_nop 0
	v_sub_f32_e32 v49, 1.0, v49
	s_andn2_saveexec_b64 s[8:9], s[8:9]
	v_fmamk_f32 v49, v52, 0x3d2aaaab, v222
	v_fma_f32 v49, v52, v49, 0.5
	v_fma_f32 v49, v52, v49, 1.0
	v_mul_f32_e64 v49, v49, -v52
	s_or_b64 exec, exec, s[8:9]
	v_sqrt_f32_e32 v49, v49
	v_mul_f32_e32 v43, 0x3fb8aa3b, v43
	v_exp_f32_e32 v43, v43
	s_mov_b64 s[8:9], 0xb083000
	s_waitcnt vmcnt(39)
	v_lshlrev_b32_e32 v47, 16, v47
	v_mul_f32_e32 v46, v46, v49
	s_waitcnt vmcnt(38)
	v_add_f32_e32 v49, v39, v39
	v_lshl_add_u64 v[52:53], v[4:5], 0, s[8:9]
	s_mov_b64 s[8:9], 0xd083000
	v_mul_f32_e32 v46, v46, v47
	v_cmp_nlt_f32_e32 vcc, s95, v49
	v_lshl_add_u64 v[54:55], v[4:5], 0, s[8:9]
	global_store_dword v[52:53], v43, off
	global_store_dword v[54:55], v46, off
	s_and_saveexec_b64 s[8:9], vcc
	s_xor_b64 s[8:9], exec, s[8:9]
	v_mul_f32_e32 v47, 0x3fb8aa3b, v49
	v_exp_f32_e32 v47, v47
	s_nop 0
	v_sub_f32_e32 v47, 1.0, v47
	s_andn2_saveexec_b64 s[8:9], s[8:9]
	v_fmamk_f32 v47, v49, 0x3d2aaaab, v222
	v_fma_f32 v47, v49, v47, 0.5
	v_fma_f32 v47, v49, v47, 1.0
	v_mul_f32_e64 v47, v47, -v49
	s_or_b64 exec, exec, s[8:9]
	v_sqrt_f32_e32 v47, v47
	v_mul_f32_e32 v39, 0x3fb8aa3b, v39
	v_exp_f32_e32 v39, v39
	s_mov_b64 s[8:9], 0xb083800
	s_waitcnt vmcnt(38)
	v_lshlrev_b32_e32 v41, 16, v41
	v_mul_f32_e32 v40, v40, v47
	s_waitcnt vmcnt(37)
	v_add_f32_e32 v47, v34, v34
	v_lshl_add_u64 v[52:53], v[4:5], 0, s[8:9]
	s_mov_b64 s[8:9], 0xd083800
	v_mul_f32_e32 v40, v40, v41
	v_cmp_nlt_f32_e32 vcc, s95, v47
	v_lshl_add_u64 v[54:55], v[4:5], 0, s[8:9]
	global_store_dword v[52:53], v39, off
	global_store_dword v[54:55], v40, off
	s_and_saveexec_b64 s[8:9], vcc
	s_xor_b64 s[8:9], exec, s[8:9]
	v_mul_f32_e32 v41, 0x3fb8aa3b, v47
	v_exp_f32_e32 v41, v41
	s_nop 0
	v_sub_f32_e32 v41, 1.0, v41
	s_andn2_saveexec_b64 s[8:9], s[8:9]
	v_fmamk_f32 v41, v47, 0x3d2aaaab, v222
	v_fma_f32 v41, v47, v41, 0.5
	v_fma_f32 v41, v47, v41, 1.0
	v_mul_f32_e64 v41, v41, -v47
	s_or_b64 exec, exec, s[8:9]
	v_sqrt_f32_e32 v41, v41
	v_mul_f32_e32 v34, 0x3fb8aa3b, v34
	v_exp_f32_e32 v34, v34
	s_mov_b64 s[8:9], 0xb084000
	s_waitcnt vmcnt(37)
; __device__ __forceinline__ float bf2f(bf16 b) { return __uint_as_float(((unsigned)b) << 16); }
; __device__ __forceinline__ void stage_lruA(const Params& P) {
;     ...
;             for (int i = 0; i < 16; ++i) { la[i] = LA[(size_t)(tb + i) * 512 + ch]; ig[i] = LBX[(size_t)(tb + i) * 512 + ch]; uc[i] = bf2f(UC[(size_t)(tb + i) * 512 + ch]); }
; #pragma unroll
;             for (int i = 0; i < 16; ++i) {
;                 const float a = __expf(la[i]), x2 = 2.f * la[i];
;                 const float em = x2 > -0.1f ? -x2 * (1.f + x2 * (0.5f + x2 * (0.16666667f + x2 * 0.041666668f))) : 1.f - __expf(x2);
;                 const float mult = (tb + i) == 0 ? 1.f : __builtin_amdgcn_sqrtf(em);
;                 const float bxv = mult * ig[i] * uc[i];
;                 hh = a * hh + bxv; ap *= a;
;                 LA[(size_t)(tb + i) * 512 + ch] = a; LBX[(size_t)(tb + i) * 512 + ch] = bxv;
	v_lshlrev_b32_e32 v38, 16, v38
	v_mul_f32_e32 v35, v35, v41
	s_waitcnt vmcnt(36)
	v_add_f32_e32 v41, v32, v32
	v_lshl_add_u64 v[52:53], v[4:5], 0, s[8:9]
	s_mov_b64 s[8:9], 0xd084000
	v_mul_f32_e32 v35, v35, v38
	v_cmp_nlt_f32_e32 vcc, s95, v41
	v_lshl_add_u64 v[54:55], v[4:5], 0, s[8:9]
	global_store_dword v[52:53], v34, off
	global_store_dword v[54:55], v35, off
	s_and_saveexec_b64 s[8:9], vcc
	s_xor_b64 s[8:9], exec, s[8:9]
	v_mul_f32_e32 v38, 0x3fb8aa3b, v41
	v_exp_f32_e32 v38, v38
	s_nop 0
	v_sub_f32_e32 v38, 1.0, v38
	s_andn2_saveexec_b64 s[8:9], s[8:9]
	v_fmamk_f32 v38, v41, 0x3d2aaaab, v222
	v_fma_f32 v38, v41, v38, 0.5
	v_fma_f32 v38, v41, v38, 1.0
	v_mul_f32_e64 v38, v38, -v41
	s_or_b64 exec, exec, s[8:9]
	v_sqrt_f32_e32 v38, v38
	v_mul_f32_e32 v32, 0x3fb8aa3b, v32
	v_exp_f32_e32 v32, v32
	s_mov_b64 s[8:9], 0xb084800
	s_waitcnt vmcnt(36)
	v_lshlrev_b32_e32 v33, 16, v33
	v_mul_f32_e32 v31, v31, v38
	s_waitcnt vmcnt(35)
	v_add_f32_e32 v38, v25, v25
	v_lshl_add_u64 v[52:53], v[4:5], 0, s[8:9]
	s_mov_b64 s[8:9], 0xd084800
	v_mul_f32_e32 v31, v31, v33
	v_cmp_nlt_f32_e32 vcc, s95, v38
	v_lshl_add_u64 v[54:55], v[4:5], 0, s[8:9]
	global_store_dword v[52:53], v32, off
	global_store_dword v[54:55], v31, off
	s_and_saveexec_b64 s[8:9], vcc
	s_xor_b64 s[8:9], exec, s[8:9]
	v_mul_f32_e32 v33, 0x3fb8aa3b, v38
	v_exp_f32_e32 v33, v33
	s_nop 0
	v_sub_f32_e32 v33, 1.0, v33
	s_andn2_saveexec_b64 s[8:9], s[8:9]
	v_fmamk_f32 v33, v38, 0x3d2aaaab, v222
	v_fma_f32 v33, v38, v33, 0.5
	v_fma_f32 v33, v38, v33, 1.0
	v_mul_f32_e64 v33, v33, -v38
	s_or_b64 exec, exec, s[8:9]
	v_sqrt_f32_e32 v33, v33
	v_mul_f32_e32 v25, 0x3fb8aa3b, v25
	v_exp_f32_e32 v25, v25
	s_mov_b64 s[8:9], 0xb085000
	s_waitcnt vmcnt(35)
	v_lshlrev_b32_e32 v30, 16, v30
	v_mul_f32_e32 v26, v26, v33
	s_waitcnt vmcnt(34)
	v_add_f32_e32 v33, v22, v22
	v_lshl_add_u64 v[52:53], v[4:5], 0, s[8:9]
	s_mov_b64 s[8:9], 0xd085000
	v_mul_f32_e32 v26, v26, v30
	v_cmp_nlt_f32_e32 vcc, s95, v33
	v_lshl_add_u64 v[54:55], v[4:5], 0, s[8:9]
	global_store_dword v[52:53], v25, off
	global_store_dword v[54:55], v26, off
	s_and_saveexec_b64 s[8:9], vcc
	s_xor_b64 s[8:9], exec, s[8:9]
	v_mul_f32_e32 v30, 0x3fb8aa3b, v33
	v_exp_f32_e32 v30, v30
	s_nop 0
	v_sub_f32_e32 v30, 1.0, v30
	s_andn2_saveexec_b64 s[8:9], s[8:9]
	v_fmamk_f32 v30, v33, 0x3d2aaaab, v222
	v_fma_f32 v30, v33, v30, 0.5
	v_fma_f32 v30, v33, v30, 1.0
	v_mul_f32_e64 v30, v30, -v33
	s_or_b64 exec, exec, s[8:9]
	v_sqrt_f32_e32 v30, v30
	v_mul_f32_e32 v22, 0x3fb8aa3b, v22
	v_exp_f32_e32 v22, v22
	s_mov_b64 s[8:9], 0xb085800
	s_waitcnt vmcnt(34)
	v_lshlrev_b32_e32 v23, 16, v23
	v_mul_f32_e32 v21, v21, v30
	s_waitcnt vmcnt(33)
	v_add_f32_e32 v30, v18, v18
	v_lshl_add_u64 v[52:53], v[4:5], 0, s[8:9]
	s_mov_b64 s[8:9], 0xd085800
	v_mul_f32_e32 v21, v21, v23
	v_cmp_nlt_f32_e32 vcc, s95, v30
	v_lshl_add_u64 v[54:55], v[4:5], 0, s[8:9]
	global_store_dword v[52:53], v22, off
	global_store_dword v[54:55], v21, off
	s_and_saveexec_b64 s[8:9], vcc
	s_xor_b64 s[8:9], exec, s[8:9]
	v_mul_f32_e32 v23, 0x3fb8aa3b, v30
	v_exp_f32_e32 v23, v23
	s_nop 0
	v_sub_f32_e32 v23, 1.0, v23
	s_andn2_saveexec_b64 s[8:9], s[8:9]
	v_fmamk_f32 v23, v30, 0x3d2aaaab, v222
	v_fma_f32 v23, v30, v23, 0.5
	v_fma_f32 v23, v30, v23, 1.0
	v_mul_f32_e64 v23, v23, -v30
	s_or_b64 exec, exec, s[8:9]
	v_sqrt_f32_e32 v23, v23
	v_mul_f32_e32 v18, 0x3fb8aa3b, v18
	v_exp_f32_e32 v18, v18
	s_waitcnt vmcnt(33)
	v_lshlrev_b32_e32 v27, 16, v27
	v_mul_f32_e32 v23, v24, v23
	s_mov_b64 s[8:9], 0xb086000
	v_mul_f32_e32 v23, v23, v27
	s_waitcnt vmcnt(32)
	v_add_f32_e32 v27, v13, v13
	v_lshl_add_u64 v[52:53], v[4:5], 0, s[8:9]
	s_mov_b64 s[8:9], 0xd086000
	v_cmp_nlt_f32_e32 vcc, s95, v27
	v_lshl_add_u64 v[54:55], v[4:5], 0, s[8:9]
	global_store_dword v[52:53], v18, off
	global_store_dword v[54:55], v23, off
	s_and_saveexec_b64 s[8:9], vcc
	s_xor_b64 s[8:9], exec, s[8:9]
	v_mul_f32_e32 v24, 0x3fb8aa3b, v27
	v_exp_f32_e32 v24, v24
	s_nop 0
	v_sub_f32_e32 v24, 1.0, v24
	s_andn2_saveexec_b64 s[8:9], s[8:9]
	v_fmamk_f32 v24, v27, 0x3d2aaaab, v222
	v_fma_f32 v24, v27, v24, 0.5
	v_fma_f32 v24, v27, v24, 1.0
	v_mul_f32_e64 v24, v24, -v27
	s_or_b64 exec, exec, s[8:9]
	v_sqrt_f32_e32 v24, v24
	v_mul_f32_e32 v13, 0x3fb8aa3b, v13
	v_exp_f32_e32 v13, v13
	s_mov_b64 s[8:9], 0xb086800
	s_waitcnt vmcnt(32)
	v_lshlrev_b32_e32 v17, 16, v17
	v_mul_f32_e32 v16, v16, v24
	s_waitcnt vmcnt(31)
	v_add_f32_e32 v24, v6, v6
	v_lshl_add_u64 v[52:53], v[4:5], 0, s[8:9]
	s_mov_b64 s[8:9], 0xd086800
	v_mul_f32_e32 v16, v16, v17
	v_cmp_nlt_f32_e32 vcc, s95, v24
	v_lshl_add_u64 v[54:55], v[4:5], 0, s[8:9]
	global_store_dword v[52:53], v13, off
	global_store_dword v[54:55], v16, off
	s_and_saveexec_b64 s[8:9], vcc
	s_xor_b64 s[8:9], exec, s[8:9]
	v_mul_f32_e32 v17, 0x3fb8aa3b, v24
	v_exp_f32_e32 v17, v17
	s_nop 0
	v_sub_f32_e32 v17, 1.0, v17
	s_andn2_saveexec_b64 s[8:9], s[8:9]
	v_fmamk_f32 v17, v24, 0x3d2aaaab, v222
	v_fma_f32 v17, v24, v17, 0.5
	v_fma_f32 v17, v24, v17, 1.0
	v_mul_f32_e64 v17, v17, -v24
	s_or_b64 exec, exec, s[8:9]
	v_sqrt_f32_e32 v24, v17
	v_mul_f32_e32 v6, 0x3fb8aa3b, v6
	v_exp_f32_e32 v17, v6
	s_mov_b64 s[8:9], 0xb087000
	s_waitcnt vmcnt(31)
	v_lshlrev_b32_e32 v6, 16, v15
	v_mul_f32_e32 v14, v14, v24
	s_waitcnt vmcnt(30)
	v_add_f32_e32 v15, v7, v7
	v_lshl_add_u64 v[52:53], v[4:5], 0, s[8:9]
	s_mov_b64 s[8:9], 0xd087000
	v_mul_f32_e32 v6, v14, v6
	v_cmp_nlt_f32_e32 vcc, s95, v15
	v_lshl_add_u64 v[54:55], v[4:5], 0, s[8:9]
	global_store_dword v[52:53], v17, off
	global_store_dword v[54:55], v6, off
	s_and_saveexec_b64 s[8:9], vcc
	s_xor_b64 s[8:9], exec, s[8:9]
	v_mul_f32_e32 v14, 0x3fb8aa3b, v15
	v_exp_f32_e32 v14, v14
	s_nop 0
	v_sub_f32_e32 v14, 1.0, v14
	s_andn2_saveexec_b64 s[8:9], s[8:9]
	s_waitcnt vmcnt(30)
	s_cbranch_execz .LBB0_278
	v_fmamk_f32 v14, v15, 0x3d2aaaab, v222
	v_fma_f32 v14, v15, v14, 0.5
	v_fma_f32 v14, v15, v14, 1.0
	v_mul_f32_e64 v14, v14, -v15
	s_branch .LBB0_278
